# v31 + phase-0 window-cache copy loop with eight loads in flight per thread instead of one
# speedup vs baseline: 1.0060x; 1.0002x over previous
.LBB0_165:
	s_load_dwordx2 s[10:11], s[0:1], 0x18
	s_ashr_i32 s39, s38, 31
	s_mov_b32 s73, 0
	s_lshl_b32 s4, s72, 9
	v_or_b32_e32 v2, s4, v0
	s_add_u32 s6, s76, 0x8500000
	s_addc_u32 s7, s77, 0
	s_lshl_b32 s8, s38, 9
	s_mov_b32 s3, 0x2040811
	s_mov_b32 s12, 0x1fbfff
	s_mov_b32 s13, 2
	s_waitcnt lgkmcnt(0)
	s_add_u32 s10, s10, 0x2000
	s_addc_u32 s11, s11, 0
.Lwcopy_loop:
	v_min_u32_e32 v4, s12, v2
	v_add_u32_e32 v2, s8, v2
	v_min_u32_e32 v5, s12, v2
	v_add_u32_e32 v2, s8, v2
	v_min_u32_e32 v6, s12, v2
	v_add_u32_e32 v2, s8, v2
	v_min_u32_e32 v7, s12, v2
	v_add_u32_e32 v2, s8, v2
	v_min_u32_e32 v8, s12, v2
	v_add_u32_e32 v2, s8, v2
	v_min_u32_e32 v9, s12, v2
	v_add_u32_e32 v2, s8, v2
	v_min_u32_e32 v10, s12, v2
	v_add_u32_e32 v2, s8, v2
	v_min_u32_e32 v11, s12, v2
	v_add_u32_e32 v2, s8, v2
	v_lshrrev_b32_e32 v12, 9, v4
	v_mul_hi_u32 v12, v12, s3
	v_mul_u32_u24_e32 v13, 0xfe00, v12
	v_sub_u32_e32 v13, v4, v13
	v_lshlrev_b32_e32 v12, 20, v12
	v_lshl_add_u32 v4, v13, 4, v12
	global_load_dwordx4 v[32:35], v4, s[10:11]
	v_lshrrev_b32_e32 v12, 9, v5
	v_mul_hi_u32 v12, v12, s3
	v_mul_u32_u24_e32 v13, 0xfe00, v12
	v_sub_u32_e32 v13, v5, v13
	v_lshlrev_b32_e32 v12, 20, v12
	v_lshl_add_u32 v5, v13, 4, v12
	global_load_dwordx4 v[36:39], v5, s[10:11]
	v_lshrrev_b32_e32 v12, 9, v6
	v_mul_hi_u32 v12, v12, s3
	v_mul_u32_u24_e32 v13, 0xfe00, v12
	v_sub_u32_e32 v13, v6, v13
	v_lshlrev_b32_e32 v12, 20, v12
	v_lshl_add_u32 v6, v13, 4, v12
	global_load_dwordx4 v[40:43], v6, s[10:11]
	v_lshrrev_b32_e32 v12, 9, v7
	v_mul_hi_u32 v12, v12, s3
	v_mul_u32_u24_e32 v13, 0xfe00, v12
	v_sub_u32_e32 v13, v7, v13
	v_lshlrev_b32_e32 v12, 20, v12
	v_lshl_add_u32 v7, v13, 4, v12
	global_load_dwordx4 v[44:47], v7, s[10:11]
	v_lshrrev_b32_e32 v12, 9, v8
	v_mul_hi_u32 v12, v12, s3
	v_mul_u32_u24_e32 v13, 0xfe00, v12
	v_sub_u32_e32 v13, v8, v13
	v_lshlrev_b32_e32 v12, 20, v12
	v_lshl_add_u32 v8, v13, 4, v12
	global_load_dwordx4 v[48:51], v8, s[10:11]
	v_lshrrev_b32_e32 v12, 9, v9
	v_mul_hi_u32 v12, v12, s3
	v_mul_u32_u24_e32 v13, 0xfe00, v12
	v_sub_u32_e32 v13, v9, v13
	v_lshlrev_b32_e32 v12, 20, v12
	v_lshl_add_u32 v9, v13, 4, v12
	global_load_dwordx4 v[52:55], v9, s[10:11]
	v_lshrrev_b32_e32 v12, 9, v10
	v_mul_hi_u32 v12, v12, s3
	v_mul_u32_u24_e32 v13, 0xfe00, v12
	v_sub_u32_e32 v13, v10, v13
	v_lshlrev_b32_e32 v12, 20, v12
	v_lshl_add_u32 v10, v13, 4, v12
	global_load_dwordx4 v[56:59], v10, s[10:11]
	v_lshrrev_b32_e32 v12, 9, v11
	v_mul_hi_u32 v12, v12, s3
	v_mul_u32_u24_e32 v13, 0xfe00, v12
	v_sub_u32_e32 v13, v11, v13
	v_lshlrev_b32_e32 v12, 20, v12
	v_lshl_add_u32 v11, v13, 4, v12
	global_load_dwordx4 v[60:63], v11, s[10:11]
	s_waitcnt vmcnt(0)
	global_store_dwordx4 v4, v[32:35], s[6:7]
	global_store_dwordx4 v5, v[36:39], s[6:7]
	global_store_dwordx4 v6, v[40:43], s[6:7]
	global_store_dwordx4 v7, v[44:47], s[6:7]
	global_store_dwordx4 v8, v[48:51], s[6:7]
	global_store_dwordx4 v9, v[52:55], s[6:7]
	global_store_dwordx4 v10, v[56:59], s[6:7]
	global_store_dwordx4 v11, v[60:63], s[6:7]
	s_sub_i32 s13, s13, 1
	s_cmp_lg_u32 s13, 0
	s_cbranch_scc1 .Lwcopy_loop
	s_mov_b64 s[4:5], exec
